# gla_b3: the 32 serialized bf16 Q/K gathers of the backward direction are issued as one batch (saddr form, AGPR destinations)
# speedup vs baseline: 1.0749x; 1.0114x over previous
.LBB0_598:
	s_or_b64 exec, exec, s[94:95]
	s_ashr_i32 s81, s80, 31
	s_lshl_b64 s[94:95], s[80:81], 16
	s_lshl_b64 s[86:87], s[70:71], 9
	s_add_u32 s71, s33, s86
	s_addc_u32 s72, s8, s87
	s_lshl_b32 s81, s3, 1
	s_add_u32 s88, s71, s81
	s_addc_u32 s89, s72, 0
	v_mov_b32_e32 v117, v65
	v_lshl_add_u64 v[2:3], s[88:89], 0, v[116:117]
	v_mov_b32_e32 v79, v65
	v_lshl_add_u64 v[6:7], v[2:3], 0, v[78:79]
	s_waitcnt lgkmcnt(0)
	s_barrier
	global_load_ushort v5, v[6:7], off
	ds_read_b32 v4, v218 offset:36096
	v_accvgpr_write_b32 a125, v7
	v_accvgpr_write_b32 a124, v6
	s_add_u32 s71, s9, s86
	s_addc_u32 s72, s10, s87
	s_waitcnt lgkmcnt(0)
	v_mul_f32_e32 v6, 0x3fb8aa3b, v4
	v_exp_f32_e32 v6, v6
	s_add_u32 s86, s71, s81
	s_addc_u32 s87, s72, 0
	v_lshl_add_u64 v[0:1], s[86:87], 0, v[116:117]
	v_add_u32_e32 v8, v116, v78
	global_load_ushort a0, v8, s[86:87]
	v_add_u32_e32 v8, v116, v80
	global_load_ushort a1, v8, s[88:89]
	v_add_u32_e32 v8, v116, v80
	global_load_ushort a2, v8, s[86:87]
	v_add_u32_e32 v8, v116, v82
	global_load_ushort a3, v8, s[88:89]
	v_add_u32_e32 v8, v116, v82
	global_load_ushort a4, v8, s[86:87]
	v_add_u32_e32 v8, v116, v84
	global_load_ushort a5, v8, s[88:89]
	v_add_u32_e32 v8, v116, v84
	global_load_ushort a6, v8, s[86:87]
	v_add_u32_e32 v8, v116, v86
	global_load_ushort a7, v8, s[88:89]
	v_add_u32_e32 v8, v116, v86
	global_load_ushort a8, v8, s[86:87]
	v_add_u32_e32 v8, v116, v88
	global_load_ushort a9, v8, s[88:89]
	v_add_u32_e32 v8, v116, v88
	global_load_ushort a10, v8, s[86:87]
	v_add_u32_e32 v8, v116, v90
	global_load_ushort a11, v8, s[88:89]
	v_add_u32_e32 v8, v116, v90
	global_load_ushort a12, v8, s[86:87]
	v_add_u32_e32 v8, v116, v92
	global_load_ushort a13, v8, s[88:89]
	v_add_u32_e32 v8, v116, v92
	global_load_ushort a14, v8, s[86:87]
	v_add_u32_e32 v8, v116, v94
	global_load_ushort a15, v8, s[88:89]
	v_add_u32_e32 v8, v116, v94
	global_load_ushort a16, v8, s[86:87]
	v_add_u32_e32 v8, v116, v96
	global_load_ushort a17, v8, s[88:89]
	v_add_u32_e32 v8, v116, v96
	global_load_ushort a18, v8, s[86:87]
	v_add_u32_e32 v8, v116, v98
	global_load_ushort a19, v8, s[88:89]
	v_add_u32_e32 v8, v116, v98
	global_load_ushort a20, v8, s[86:87]
	v_add_u32_e32 v8, v116, v100
	global_load_ushort a21, v8, s[88:89]
	v_add_u32_e32 v8, v116, v108
	global_load_ushort a22, v8, s[88:89]
	v_add_u32_e32 v8, v116, v100
	global_load_ushort a23, v8, s[86:87]
	v_add_u32_e32 v8, v116, v102
	global_load_ushort a24, v8, s[88:89]
	v_add_u32_e32 v8, v116, v102
	global_load_ushort a25, v8, s[86:87]
	v_add_u32_e32 v8, v116, v104
	global_load_ushort a26, v8, s[88:89]
	v_add_u32_e32 v8, v116, v108
	global_load_ushort a27, v8, s[86:87]
	v_add_u32_e32 v8, v116, v104
	global_load_ushort a28, v8, s[86:87]
	v_add_u32_e32 v8, v116, v106
	global_load_ushort a29, v8, s[88:89]
	v_add_u32_e32 v8, v116, v106
	global_load_ushort a30, v8, s[86:87]
	v_mov_b32_e32 v81, v65
	v_mul_f32_e32 v4, 0xbfb8aa3b, v4
	v_exp_f32_e32 v4, v4
	v_mov_b32_e32 v83, v65
	v_lshl_add_u64 v[188:189], v[0:1], 0, v[82:83]
	v_mov_b32_e32 v85, v65
	v_lshl_add_u64 v[190:191], v[2:3], 0, v[84:85]
	v_lshl_add_u64 v[192:193], v[0:1], 0, v[84:85]
	v_mov_b32_e32 v87, v65
	v_lshl_add_u64 v[194:195], v[2:3], 0, v[86:87]
	v_lshl_add_u64 v[196:197], v[0:1], 0, v[86:87]
	v_mov_b32_e32 v89, v65
	v_accvgpr_write_b32 a60, v218
	v_accvgpr_write_b32 a62, v219
	v_lshl_add_u64 v[214:215], v[0:1], 0, v[88:89]
	v_mov_b32_e32 v91, v65
	v_lshl_add_u64 v[222:223], v[2:3], 0, v[90:91]
	v_lshl_add_u64 v[224:225], v[0:1], 0, v[90:91]
	v_mov_b32_e32 v93, v65
	v_accvgpr_write_b32 a117, v226
	v_lshl_add_u64 v[228:229], v[0:1], 0, v[92:93]
	v_accvgpr_write_b32 a48, v95
	v_accvgpr_write_b32 a49, v97
	v_accvgpr_write_b32 a50, v99
	v_accvgpr_write_b32 a51, v101
	v_accvgpr_write_b32 a55, v109
	v_accvgpr_write_b32 a52, v103
	v_accvgpr_write_b32 a53, v105
	v_accvgpr_write_b32 a54, v107
	v_accvgpr_write_b32 a56, v206
	v_accvgpr_write_b32 a118, v210
	v_accvgpr_write_b32 a57, v207
	v_accvgpr_write_b32 a119, v211
	v_accvgpr_write_b32 a58, v208
	v_accvgpr_write_b32 a59, v209
	v_accvgpr_write_b32 a120, v212
	v_accvgpr_read_b32 v32, a68
	v_accvgpr_read_b32 v33, a69
	v_lshl_add_u64 v[56:57], v[32:33], 0, s[94:95]
	v_mov_b32_e32 v119, v65
	v_mov_b32_e32 v121, v65
	v_mov_b32_e32 v143, v65
	v_lshl_add_u64 v[32:33], v[56:57], 0, v[118:119]
	v_lshl_add_u64 v[44:45], v[56:57], 0, v[120:121]
	v_mov_b32_e32 v123, v65
	v_lshl_add_u64 v[48:49], v[56:57], 0, v[142:143]
	v_mov_b32_e32 v145, v65
	v_mov_b32_e32 v125, v65
	v_mov_b32_e32 v147, v65
	v_mov_b32_e32 v127, v65
	v_mov_b32_e32 v151, v65
	v_mov_b32_e32 v135, v65
	v_mov_b32_e32 v153, v65
	v_mov_b32_e32 v137, v65
	v_mov_b32_e32 v155, v65
	v_mov_b32_e32 v139, v65
	v_mov_b32_e32 v157, v65
	v_mov_b32_e32 v141, v65
	v_mov_b32_e32 v159, v65
	v_mov_b32_e32 v161, v65
	v_lshl_add_u64 v[58:59], v[56:57], 0, v[160:161]
	v_mov_b32_e32 v163, v65
	v_accvgpr_read_b32 v70, a70
	v_mov_b32_e32 v165, v65
	s_lshl_b32 s72, s3, 2
	v_accvgpr_read_b32 v71, a71
	v_mov_b32_e32 v167, v65
	v_lshl_add_u64 v[246:247], v[70:71], 0, s[72:73]
	s_movk_i32 s3, 0x1000
	s_waitcnt vmcnt(0)
	v_lshlrev_b32_e32 v5, 16, v5
	v_mul_f32_e32 v5, v6, v5
	v_cvt_pk_bf16_f32 v5, v5, s0
	v_lshl_add_u64 v[6:7], v[0:1], 0, v[78:79]
	ds_write_b16 v95, v5 offset:52736
	s_waitcnt vmcnt(0)
	v_accvgpr_read_b32 v5, a0
	v_accvgpr_write_b32 a127, v7
	v_accvgpr_write_b32 a126, v6
	v_lshl_add_u64 v[6:7], v[2:3], 0, v[80:81]
	v_accvgpr_write_b32 a129, v7
	v_accvgpr_write_b32 a128, v6
	v_accvgpr_read_b32 v6, a1
	v_accvgpr_write_b32 a61, v242
	v_mov_b32_e32 v169, v65
	v_accvgpr_write_b32 a63, v243
	v_mov_b32_e32 v171, v65
	v_mov_b32_e32 v173, v65
	v_mov_b32_e32 v175, v65
	v_lshlrev_b32_e32 v70, 2, v184
	v_accvgpr_write_b32 a116, v244
	s_mov_b64 s[96:97], 0
	s_waitcnt vmcnt(1)
	v_lshlrev_b32_e32 v5, 16, v5
	v_mul_f32_e32 v4, v4, v5
	v_cvt_pk_bf16_f32 v4, v4, s0
	ds_write_b16 v95, v4 offset:61952
	ds_read2_b32 v[4:5], v219 offset0:64 offset1:129
	v_lshl_add_u64 v[218:219], v[2:3], 0, v[88:89]
	s_waitcnt vmcnt(0)
	v_lshlrev_b32_e32 v6, 16, v6
	v_mov_b32_e32 v95, v65
	v_lshl_add_u64 v[230:231], v[2:3], 0, v[94:95]
	s_waitcnt lgkmcnt(0)
	v_mul_f32_e32 v7, 0x3fb8aa3b, v4
	v_exp_f32_e32 v7, v7
	v_mul_f32_e32 v4, 0xbfb8aa3b, v4
	v_exp_f32_e32 v4, v4
	v_lshl_add_u64 v[232:233], v[0:1], 0, v[94:95]
	v_mul_f32_e32 v6, v7, v6
	v_cvt_pk_bf16_f32 v6, v6, s0
	ds_write_b16 v97, v6 offset:52736
	v_lshl_add_u64 v[6:7], v[0:1], 0, v[80:81]
	v_accvgpr_write_b32 a131, v7
	v_accvgpr_write_b32 a130, v6
	v_accvgpr_read_b32 v6, a2
	s_waitcnt vmcnt(0)
	v_lshlrev_b32_e32 v6, 16, v6
	v_mul_f32_e32 v4, v4, v6
	v_cvt_pk_bf16_f32 v4, v4, s0
	v_lshl_add_u64 v[6:7], v[2:3], 0, v[82:83]
	ds_write_b16 v97, v4 offset:61952
	v_accvgpr_read_b32 v4, a3
	v_accvgpr_write_b32 a135, v7
	v_accvgpr_write_b32 a134, v6
	v_mul_f32_e32 v6, 0x3fb8aa3b, v5
	v_exp_f32_e32 v6, v6
	v_mul_f32_e32 v5, 0xbfb8aa3b, v5
	v_exp_f32_e32 v5, v5
	v_mov_b32_e32 v97, v65
	v_lshl_add_u64 v[234:235], v[2:3], 0, v[96:97]
	v_lshl_add_u64 v[236:237], v[0:1], 0, v[96:97]
	s_waitcnt vmcnt(0)
	v_lshlrev_b32_e32 v4, 16, v4
	v_mul_f32_e32 v4, v6, v4
	v_cvt_pk_bf16_f32 v4, v4, s0
	ds_write_b16 v99, v4 offset:52736
	v_accvgpr_read_b32 v4, a4
	v_accvgpr_read_b32 v6, a5
	s_waitcnt vmcnt(1)
	v_lshlrev_b32_e32 v4, 16, v4
	v_mul_f32_e32 v4, v5, v4
	v_cvt_pk_bf16_f32 v4, v4, s0
	ds_write_b16 v99, v4 offset:61952
	ds_read2_b32 v[4:5], v243 offset0:66 offset1:131
	s_waitcnt vmcnt(0)
	v_lshlrev_b32_e32 v6, 16, v6
	v_mov_b32_e32 v99, v65
	v_lshl_add_u64 v[198:199], v[2:3], 0, v[98:99]
	v_lshl_add_u64 v[200:201], v[0:1], 0, v[98:99]
	s_waitcnt lgkmcnt(0)
	v_mul_f32_e32 v7, 0x3fb8aa3b, v4
	v_exp_f32_e32 v7, v7
	v_mul_f32_e32 v4, 0xbfb8aa3b, v4
	v_exp_f32_e32 v4, v4
	v_mul_f32_e32 v6, v7, v6
	v_cvt_pk_bf16_f32 v6, v6, s0
	ds_write_b16 v101, v6 offset:52736
	v_accvgpr_read_b32 v6, a6
	s_waitcnt vmcnt(0)
	v_lshlrev_b32_e32 v6, 16, v6
	v_mul_f32_e32 v4, v4, v6
	v_cvt_pk_bf16_f32 v4, v4, s0
	ds_write_b16 v101, v4 offset:61952
	v_accvgpr_read_b32 v4, a7
	v_mul_f32_e32 v6, 0x3fb8aa3b, v5
	v_exp_f32_e32 v6, v6
	v_mul_f32_e32 v5, 0xbfb8aa3b, v5
	v_exp_f32_e32 v5, v5
	v_mov_b32_e32 v101, v65
	v_lshl_add_u64 v[202:203], v[2:3], 0, v[100:101]
	v_lshl_add_u64 v[204:205], v[0:1], 0, v[100:101]
	s_waitcnt vmcnt(0)
	v_lshlrev_b32_e32 v4, 16, v4
	v_mul_f32_e32 v4, v6, v4
	v_cvt_pk_bf16_f32 v4, v4, s0
	ds_write_b16 v103, v4 offset:52736
	v_accvgpr_read_b32 v4, a8
	v_accvgpr_read_b32 v6, a9
	s_waitcnt vmcnt(1)
	v_lshlrev_b32_e32 v4, 16, v4
	v_mul_f32_e32 v4, v5, v4
	v_cvt_pk_bf16_f32 v4, v4, s0
	ds_write_b16 v103, v4 offset:61952
	ds_read2_b32 v[4:5], v244 offset0:68 offset1:133
	s_waitcnt vmcnt(0)
	v_lshlrev_b32_e32 v6, 16, v6
	v_mov_b32_e32 v103, v65
	s_waitcnt lgkmcnt(0)
	v_mul_f32_e32 v7, 0x3fb8aa3b, v4
	v_exp_f32_e32 v7, v7
	v_mul_f32_e32 v4, 0xbfb8aa3b, v4
	v_exp_f32_e32 v4, v4
	v_mul_f32_e32 v6, v7, v6
	v_cvt_pk_bf16_f32 v6, v6, s0
	ds_write_b16 v105, v6 offset:52736
	v_accvgpr_read_b32 v6, a10
	s_waitcnt vmcnt(0)
	v_lshlrev_b32_e32 v6, 16, v6
	v_mul_f32_e32 v4, v4, v6
	v_cvt_pk_bf16_f32 v4, v4, s0
	ds_write_b16 v105, v4 offset:61952
	v_accvgpr_read_b32 v4, a11
	v_mul_f32_e32 v6, 0x3fb8aa3b, v5
	v_exp_f32_e32 v6, v6
	v_mul_f32_e32 v5, 0xbfb8aa3b, v5
	v_exp_f32_e32 v5, v5
	v_mov_b32_e32 v105, v65
	s_waitcnt vmcnt(0)
	v_lshlrev_b32_e32 v4, 16, v4
	v_mul_f32_e32 v4, v6, v4
	v_cvt_pk_bf16_f32 v4, v4, s0
	ds_write_b16 v107, v4 offset:52736
	v_accvgpr_read_b32 v4, a12
	s_waitcnt vmcnt(0)
	v_lshlrev_b32_e32 v4, 16, v4
	v_mul_f32_e32 v4, v5, v4
	v_cvt_pk_bf16_f32 v4, v4, s0
	ds_write_b16 v107, v4 offset:61952
	ds_read2_b32 v[4:5], v226 offset0:70 offset1:135
	v_lshl_add_u64 v[226:227], v[2:3], 0, v[92:93]
	v_accvgpr_read_b32 v6, a13
	v_mov_b32_e32 v107, v65
	v_lshl_add_u64 v[216:217], v[2:3], 0, v[106:107]
	s_waitcnt lgkmcnt(0)
	v_mul_f32_e32 v7, 0x3fb8aa3b, v4
	v_exp_f32_e32 v7, v7
	v_mul_f32_e32 v4, 0xbfb8aa3b, v4
	v_exp_f32_e32 v4, v4
	v_lshl_add_u64 v[220:221], v[0:1], 0, v[106:107]
	s_waitcnt vmcnt(0)
	v_lshlrev_b32_e32 v6, 16, v6
	v_mul_f32_e32 v6, v7, v6
	v_cvt_pk_bf16_f32 v6, v6, s0
	ds_write_b16 v109, v6 offset:52736
	v_accvgpr_read_b32 v6, a14
	s_waitcnt vmcnt(0)
	v_lshlrev_b32_e32 v6, 16, v6
	v_mul_f32_e32 v4, v4, v6
	v_cvt_pk_bf16_f32 v4, v4, s0
	ds_write_b16 v109, v4 offset:61952
	v_accvgpr_read_b32 v4, a15
	v_mul_f32_e32 v6, 0x3fb8aa3b, v5
	v_exp_f32_e32 v6, v6
	v_mul_f32_e32 v5, 0xbfb8aa3b, v5
	v_exp_f32_e32 v5, v5
	v_mov_b32_e32 v109, v65
	v_lshl_add_u64 v[238:239], v[2:3], 0, v[108:109]
	v_lshl_add_u64 v[240:241], v[0:1], 0, v[108:109]
	s_waitcnt vmcnt(0)
	v_lshlrev_b32_e32 v4, 16, v4
	v_mul_f32_e32 v4, v6, v4
	v_cvt_pk_bf16_f32 v4, v4, s0
	ds_write_b16 v206, v4 offset:52736
	v_accvgpr_read_b32 v4, a16
	v_accvgpr_read_b32 v6, a17
	s_waitcnt vmcnt(1)
	v_lshlrev_b32_e32 v4, 16, v4
	v_mul_f32_e32 v4, v5, v4
	v_cvt_pk_bf16_f32 v4, v4, s0
	ds_write_b16 v206, v4 offset:61952
	ds_read2_b32 v[4:5], v210 offset0:72 offset1:137
	s_waitcnt vmcnt(0)
	v_lshlrev_b32_e32 v6, 16, v6
	s_waitcnt lgkmcnt(0)
	v_mul_f32_e32 v7, 0x3fb8aa3b, v4
	v_exp_f32_e32 v7, v7
	v_mul_f32_e32 v4, 0xbfb8aa3b, v4
	v_exp_f32_e32 v4, v4
	v_mul_f32_e32 v6, v7, v6
	v_cvt_pk_bf16_f32 v6, v6, s0
	ds_write_b16 v207, v6 offset:52736
	v_accvgpr_read_b32 v6, a18
	s_waitcnt vmcnt(0)
	v_lshlrev_b32_e32 v6, 16, v6
	v_mul_f32_e32 v4, v4, v6
	v_cvt_pk_bf16_f32 v4, v4, s0
	ds_write_b16 v207, v4 offset:61952
	v_accvgpr_read_b32 v4, a19
	v_mul_f32_e32 v6, 0x3fb8aa3b, v5
	v_exp_f32_e32 v6, v6
	v_mul_f32_e32 v5, 0xbfb8aa3b, v5
	v_exp_f32_e32 v5, v5
	v_lshl_add_u64 v[206:207], v[2:3], 0, v[102:103]
	s_waitcnt vmcnt(0)
	v_lshlrev_b32_e32 v4, 16, v4
	v_mul_f32_e32 v4, v6, v4
	v_cvt_pk_bf16_f32 v4, v4, s0
	ds_write_b16 v208, v4 offset:52736
	v_accvgpr_read_b32 v4, a20
	v_accvgpr_read_b32 v6, a21
	s_waitcnt vmcnt(1)
	v_lshlrev_b32_e32 v4, 16, v4
	v_mul_f32_e32 v4, v5, v4
	v_cvt_pk_bf16_f32 v4, v4, s0
	ds_write_b16 v208, v4 offset:61952
	ds_read2_b32 v[4:5], v211 offset0:74 offset1:139
	s_waitcnt vmcnt(0)
	v_lshlrev_b32_e32 v6, 16, v6
	v_lshl_add_u64 v[210:211], v[2:3], 0, v[104:105]
	v_accvgpr_read_b32 v2, a22
	s_waitcnt lgkmcnt(0)
	v_mul_f32_e32 v7, 0x3fb8aa3b, v4
	v_exp_f32_e32 v7, v7
	v_mul_f32_e32 v4, 0xbfb8aa3b, v4
	v_exp_f32_e32 v4, v4
	v_mul_f32_e32 v6, v7, v6
	v_cvt_pk_bf16_f32 v6, v6, s0
	ds_write_b16 v209, v6 offset:52736
	v_accvgpr_read_b32 v6, a23
	s_waitcnt vmcnt(1)
	v_lshlrev_b32_e32 v2, 16, v2
	s_waitcnt vmcnt(0)
	v_lshlrev_b32_e32 v6, 16, v6
	v_mul_f32_e32 v4, v4, v6
	v_cvt_pk_bf16_f32 v4, v4, s0
	ds_write_b16 v209, v4 offset:61952
	v_accvgpr_read_b32 v4, a24
	v_mul_f32_e32 v6, 0x3fb8aa3b, v5
	v_exp_f32_e32 v6, v6
	v_lshl_add_u64 v[208:209], v[0:1], 0, v[102:103]
	v_mul_f32_e32 v5, 0xbfb8aa3b, v5
	v_exp_f32_e32 v5, v5
	s_waitcnt vmcnt(0)
	v_lshlrev_b32_e32 v4, 16, v4
	v_mul_f32_e32 v4, v6, v4
	v_cvt_pk_bf16_f32 v4, v4, s0
	ds_write_b16 v69, v4 offset:52736
	v_accvgpr_read_b32 v4, a25
	v_accvgpr_read_b32 v6, a26
	s_waitcnt vmcnt(1)
	v_lshlrev_b32_e32 v4, 16, v4
	v_mul_f32_e32 v4, v5, v4
	v_cvt_pk_bf16_f32 v4, v4, s0
	ds_write_b16 v69, v4 offset:61952
	ds_read2_b32 v[4:5], v212 offset0:76 offset1:141
	s_waitcnt vmcnt(0)
	v_lshlrev_b32_e32 v6, 16, v6
	v_lshl_add_u64 v[212:213], v[0:1], 0, v[104:105]
	v_accvgpr_read_b32 v0, a27
	s_waitcnt lgkmcnt(0)
	v_mul_f32_e32 v7, 0x3fb8aa3b, v4
	v_exp_f32_e32 v7, v7
	v_mul_f32_e32 v4, 0xbfb8aa3b, v4
	v_exp_f32_e32 v4, v4
	v_mul_f32_e32 v6, v7, v6
	v_cvt_pk_bf16_f32 v6, v6, s0
	ds_write_b16 v253, v6 offset:52736
	v_accvgpr_read_b32 v6, a28
	s_waitcnt vmcnt(1)
	v_lshlrev_b32_e32 v0, 16, v0
	s_waitcnt vmcnt(0)
	v_lshlrev_b32_e32 v6, 16, v6
	v_mul_f32_e32 v4, v4, v6
	v_cvt_pk_bf16_f32 v4, v4, s0
	ds_write_b16 v253, v4 offset:61952
	v_accvgpr_read_b32 v4, a29
	v_mul_f32_e32 v6, 0x3fb8aa3b, v5
	v_exp_f32_e32 v6, v6
	v_mul_f32_e32 v5, 0xbfb8aa3b, v5
	v_exp_f32_e32 v5, v5
	s_waitcnt vmcnt(0)
	v_lshlrev_b32_e32 v4, 16, v4
	v_mul_f32_e32 v4, v6, v4
	v_cvt_pk_bf16_f32 v4, v4, s0
	ds_write_b16 v254, v4 offset:52736
	v_accvgpr_read_b32 v4, a30
	s_waitcnt vmcnt(0)
	v_lshlrev_b32_e32 v4, 16, v4
	v_mul_f32_e32 v4, v5, v4
	v_cvt_pk_bf16_f32 v4, v4, s0
	ds_write_b16 v254, v4 offset:61952
	ds_read_b32 v4, v242 offset:39736
	v_add_co_u32_e32 v242, vcc, s3, v246
	s_waitcnt lgkmcnt(0)
	v_mul_f32_e32 v3, 0x3fb8aa3b, v4
	v_mul_f32_e32 v1, 0xbfb8aa3b, v4
	v_exp_f32_e32 v3, v3
	v_exp_f32_e32 v1, v1
	v_addc_co_u32_e32 v243, vcc, 0, v247, vcc
	v_mul_f32_e32 v2, v3, v2
	v_mul_f32_e32 v0, v1, v0
	v_cvt_pk_bf16_f32 v2, v2, s0
	v_cvt_pk_bf16_f32 v0, v0, s0
	ds_write_b16 v250, v2 offset:52736
	ds_write_b16 v250, v0 offset:61952
	s_waitcnt lgkmcnt(0)
	s_barrier
	ds_read_b128 v[4:7], v133 offset:52736
	ds_read_b128 v[0:3], v133 offset:52768
	ds_read_b128 v[24:27], v251 offset:61952
	ds_read_b128 v[12:15], v251 offset:61984
	ds_read_b128 v[8:11], v133 offset:52800
	ds_read_b128 v[16:19], v251 offset:62016
	ds_read_b128 v[20:23], v133 offset:52832
	ds_read_b128 v[28:31], v251 offset:62048
	global_load_dword v79, v[32:33], off
	global_load_dword v81, v[32:33], off offset:512
	global_load_dword v83, v[32:33], off offset:1024
	global_load_dword v85, v[32:33], off offset:1536
	global_load_dword v87, v[32:33], off offset:2048
	global_load_dword v89, v[32:33], off offset:2560
	global_load_dword v91, v[32:33], off offset:3072
	global_load_dword v93, v[32:33], off offset:3584
	ds_read_b128 v[36:39], v66 offset:52736
	ds_read_b128 v[32:35], v66 offset:52768
	ds_read_b128 v[40:43], v66 offset:57344
	global_load_dword v95, v[44:45], off
	global_load_dword v111, v[48:49], off
	v_lshl_add_u64 v[44:45], v[56:57], 0, v[122:123]
	v_lshl_add_u64 v[48:49], v[56:57], 0, v[144:145]
	global_load_dword v97, v[44:45], off
	global_load_dword v113, v[48:49], off
	v_lshl_add_u64 v[44:45], v[56:57], 0, v[124:125]
	v_lshl_add_u64 v[48:49], v[56:57], 0, v[146:147]
	global_load_dword v99, v[44:45], off
	global_load_dword v117, v[48:49], off
	v_lshl_add_u64 v[44:45], v[56:57], 0, v[126:127]
	v_lshl_add_u64 v[48:49], v[56:57], 0, v[150:151]
	global_load_dword v101, v[44:45], off
	global_load_dword v119, v[48:49], off
	v_lshl_add_u64 v[44:45], v[56:57], 0, v[134:135]
	v_lshl_add_u64 v[48:49], v[56:57], 0, v[152:153]
	global_load_dword v103, v[44:45], off
	global_load_dword v121, v[48:49], off
	v_lshl_add_u64 v[44:45], v[56:57], 0, v[136:137]
	v_lshl_add_u64 v[48:49], v[56:57], 0, v[154:155]
	global_load_dword v105, v[44:45], off
	global_load_dword v123, v[48:49], off
	v_lshl_add_u64 v[44:45], v[56:57], 0, v[138:139]
	v_lshl_add_u64 v[48:49], v[56:57], 0, v[156:157]
	global_load_dword v107, v[44:45], off
	global_load_dword v125, v[48:49], off
	v_lshl_add_u64 v[44:45], v[56:57], 0, v[140:141]
	v_lshl_add_u64 v[48:49], v[56:57], 0, v[158:159]
	global_load_dword v109, v[44:45], off
	global_load_dword v127, v[48:49], off
	ds_read_b128 v[44:47], v66 offset:57376
	ds_read_b128 v[52:55], v66 offset:52800
	ds_read_b128 v[48:51], v66 offset:57408
	global_load_dword v135, v[58:59], off
	v_lshl_add_u64 v[58:59], v[56:57], 0, v[162:163]
	global_load_dword v137, v[58:59], off
	v_lshl_add_u64 v[58:59], v[56:57], 0, v[164:165]
	global_load_dword v139, v[58:59], off
	v_lshl_add_u64 v[58:59], v[56:57], 0, v[166:167]
	global_load_dword v141, v[58:59], off
	v_lshl_add_u64 v[58:59], v[56:57], 0, v[168:169]
	global_load_dword v143, v[58:59], off
	v_lshl_add_u64 v[58:59], v[56:57], 0, v[170:171]
	v_add_co_u32_e32 v248, vcc, s11, v246
	global_load_dword v145, v[58:59], off
	v_lshl_add_u64 v[58:59], v[56:57], 0, v[172:173]
	v_lshl_add_u64 v[56:57], v[56:57], 0, v[174:175]
	v_addc_co_u32_e32 v249, vcc, 0, v247, vcc
	global_load_dword v147, v[58:59], off
	global_load_dword v148, v[56:57], off
	ds_read_b128 v[60:63], v66 offset:52832
	ds_read_b128 v[56:59], v66 offset:57440
	s_waitcnt lgkmcnt(0)
	s_barrier
	global_load_dword v149, v70, s[82:83]
	global_load_dword v151, v[246:247], off
	global_load_dword v153, v[246:247], off offset:1024
	global_load_dword v155, v[246:247], off offset:2048
	global_load_dword v157, v[246:247], off offset:3072
	global_load_dword v159, v[248:249], off offset:-4096
	global_load_dword v161, v[242:243], off offset:1024
	global_load_dword v184, v[242:243], off offset:2048
	global_load_dword v185, v[242:243], off offset:3072
	s_nop 0
	global_load_dword v242, v[248:249], off
	global_load_dword v243, v[248:249], off offset:1024
	global_load_dword v244, v[248:249], off offset:2048
	global_load_dword v245, v[248:249], off offset:3072
	v_add_co_u32_e32 v70, vcc, 0x3000, v246
	v_accvgpr_read_b32 v163, a78
	s_nop 0
	v_addc_co_u32_e32 v71, vcc, 0, v247, vcc
	global_load_dword v246, v[70:71], off
	global_load_dword v247, v[70:71], off offset:1024
	global_load_dword v248, v[70:71], off offset:2048
	global_load_dword v249, v[70:71], off offset:3072
	v_accvgpr_read_b32 v165, a75
	v_accvgpr_read_b32 v167, a77

.LBB0_1786:
	s_or_b64 exec, exec, s[76:77]
	s_ashr_i32 s73, s72, 31
	s_lshl_b64 s[76:77], s[72:73], 16
	s_lshl_b64 s[80:81], s[74:75], 9
	s_add_u32 s73, s33, s80
	s_addc_u32 s75, s10, s81
	s_lshl_b32 s87, s5, 1
	s_add_u32 s94, s73, s87
	s_addc_u32 s95, s75, 0
	v_mov_b32_e32 v67, v65
	v_accvgpr_read_b32 v8, a84
	v_lshl_add_u64 v[2:3], s[94:95], 0, v[66:67]
	v_accvgpr_read_b32 v9, a85
	v_lshl_add_u64 v[188:189], v[2:3], 0, v[8:9]
	s_waitcnt lgkmcnt(0)
	s_barrier
	global_load_ushort v5, v[188:189], off
	ds_read_b32 v4, v206 offset:36096
	s_add_u32 s73, s11, s80
	s_addc_u32 s75, s12, s81
	s_add_u32 s80, s73, s87
	s_addc_u32 s81, s75, 0
	s_waitcnt lgkmcnt(0)
	v_mul_f32_e32 v6, 0x3fb8aa3b, v4
	v_exp_f32_e32 v6, v6
	v_lshl_add_u64 v[0:1], s[80:81], 0, v[66:67]
	v_accvgpr_read_b32 v10, a84
	v_add_u32_e32 v10, v66, v10
	global_load_ushort a0, v10, s[80:81]
	v_add_u32_e32 v10, v66, v84
	global_load_ushort a1, v10, s[94:95]
	v_add_u32_e32 v10, v66, v84
	global_load_ushort a2, v10, s[80:81]
	v_accvgpr_read_b32 v10, a86
	v_add_u32_e32 v10, v66, v10
	global_load_ushort a3, v10, s[94:95]
	v_accvgpr_read_b32 v10, a86
	v_add_u32_e32 v10, v66, v10
	global_load_ushort a4, v10, s[80:81]
	v_accvgpr_read_b32 v10, a88
	v_add_u32_e32 v10, v66, v10
	global_load_ushort a5, v10, s[94:95]
	v_accvgpr_read_b32 v10, a88
	v_add_u32_e32 v10, v66, v10
	global_load_ushort a6, v10, s[80:81]
	v_accvgpr_read_b32 v10, a90
	v_add_u32_e32 v10, v66, v10
	global_load_ushort a7, v10, s[94:95]
	v_accvgpr_read_b32 v10, a90
	v_add_u32_e32 v10, v66, v10
	global_load_ushort a8, v10, s[80:81]
	v_accvgpr_read_b32 v10, a92
	v_add_u32_e32 v10, v66, v10
	global_load_ushort a9, v10, s[94:95]
	v_accvgpr_read_b32 v10, a92
	v_add_u32_e32 v10, v66, v10
	global_load_ushort a10, v10, s[80:81]
	v_accvgpr_read_b32 v10, a94
	v_add_u32_e32 v10, v66, v10
	global_load_ushort a11, v10, s[94:95]
	v_accvgpr_read_b32 v10, a94
	v_add_u32_e32 v10, v66, v10
	global_load_ushort a12, v10, s[80:81]
	v_accvgpr_read_b32 v10, a96
	v_add_u32_e32 v10, v66, v10
	global_load_ushort a13, v10, s[94:95]
	v_accvgpr_read_b32 v10, a96
	v_add_u32_e32 v10, v66, v10
	global_load_ushort a14, v10, s[80:81]
	v_accvgpr_read_b32 v10, a98
	v_add_u32_e32 v10, v66, v10
	global_load_ushort a15, v10, s[94:95]
	v_accvgpr_read_b32 v10, a98
	v_add_u32_e32 v10, v66, v10
	global_load_ushort a16, v10, s[80:81]
	v_accvgpr_read_b32 v10, a100
	v_add_u32_e32 v10, v66, v10
	global_load_ushort a17, v10, s[94:95]
	v_accvgpr_read_b32 v10, a100
	v_add_u32_e32 v10, v66, v10
	global_load_ushort a18, v10, s[80:81]
	v_accvgpr_read_b32 v10, a102
	v_add_u32_e32 v10, v66, v10
	global_load_ushort a19, v10, s[94:95]
	v_accvgpr_read_b32 v10, a102
	v_add_u32_e32 v10, v66, v10
	global_load_ushort a20, v10, s[80:81]
	v_accvgpr_read_b32 v10, a104
	v_add_u32_e32 v10, v66, v10
	global_load_ushort a21, v10, s[94:95]
	v_accvgpr_read_b32 v10, a104
	v_add_u32_e32 v10, v66, v10
	global_load_ushort a22, v10, s[80:81]
	v_accvgpr_read_b32 v10, a106
	v_add_u32_e32 v10, v66, v10
	global_load_ushort a23, v10, s[94:95]
	v_accvgpr_read_b32 v10, a106
	v_add_u32_e32 v10, v66, v10
	global_load_ushort a24, v10, s[80:81]
	v_accvgpr_read_b32 v10, a108
	v_add_u32_e32 v10, v66, v10
	global_load_ushort a25, v10, s[94:95]
	v_accvgpr_read_b32 v10, a108
	v_add_u32_e32 v10, v66, v10
	global_load_ushort a26, v10, s[80:81]
	v_accvgpr_read_b32 v10, a110
	v_add_u32_e32 v10, v66, v10
	global_load_ushort a27, v10, s[94:95]
	v_accvgpr_read_b32 v10, a110
	v_add_u32_e32 v10, v66, v10
	global_load_ushort a28, v10, s[80:81]
	v_accvgpr_read_b32 v10, a112
	v_add_u32_e32 v10, v66, v10
	global_load_ushort a29, v10, s[94:95]
	v_accvgpr_read_b32 v10, a112
	v_add_u32_e32 v10, v66, v10
	global_load_ushort a30, v10, s[80:81]
	v_lshl_add_u64 v[190:191], v[0:1], 0, v[8:9]
	v_mov_b32_e32 v85, v65
	v_lshl_add_u64 v[192:193], v[2:3], 0, v[84:85]
	v_mul_f32_e32 v4, 0xbfb8aa3b, v4
	v_exp_f32_e32 v4, v4
	v_lshl_add_u64 v[194:195], v[0:1], 0, v[84:85]
	v_accvgpr_read_b32 v8, a86
	v_accvgpr_read_b32 v9, a87
	v_lshl_add_u64 v[198:199], v[2:3], 0, v[8:9]
	v_accvgpr_write_b32 a54, v206
	v_lshl_add_u64 v[206:207], v[0:1], 0, v[8:9]
	v_accvgpr_read_b32 v8, a88
	v_accvgpr_read_b32 v9, a89
	v_lshl_add_u64 v[222:223], v[2:3], 0, v[8:9]
	v_lshl_add_u64 v[224:225], v[0:1], 0, v[8:9]
	v_accvgpr_read_b32 v8, a90
	v_accvgpr_read_b32 v9, a91
	v_accvgpr_write_b32 a49, v226
	v_lshl_add_u64 v[232:233], v[0:1], 0, v[8:9]
	v_accvgpr_write_b32 a50, v228
	v_accvgpr_write_b32 a51, v202
	v_accvgpr_write_b32 a52, v203
	v_accvgpr_write_b32 a53, v204
	v_accvgpr_read_b32 v32, a70
	v_accvgpr_read_b32 v33, a71
	v_lshl_add_u64 v[56:57], v[32:33], 0, s[76:77]
	v_mov_b32_e32 v119, v65
	v_mov_b32_e32 v121, v65
	v_mov_b32_e32 v157, v65
	v_lshl_add_u64 v[32:33], v[56:57], 0, v[118:119]
	v_lshl_add_u64 v[44:45], v[56:57], 0, v[120:121]
	v_mov_b32_e32 v123, v65
	v_lshl_add_u64 v[48:49], v[56:57], 0, v[156:157]
	v_mov_b32_e32 v159, v65
	v_mov_b32_e32 v125, v65
	v_mov_b32_e32 v161, v65
	v_mov_b32_e32 v127, v65
	v_mov_b32_e32 v163, v65
	v_mov_b32_e32 v149, v65
	v_mov_b32_e32 v165, v65
	v_mov_b32_e32 v151, v65
	v_mov_b32_e32 v167, v65
	v_mov_b32_e32 v153, v65
	v_mov_b32_e32 v169, v65
	v_mov_b32_e32 v155, v65
	v_mov_b32_e32 v171, v65
	v_mov_b32_e32 v173, v65
	v_lshl_add_u64 v[58:59], v[56:57], 0, v[172:173]
	v_mov_b32_e32 v175, v65
	v_accvgpr_read_b32 v75, a73
	v_mov_b32_e32 v177, v65
	s_lshl_b32 s88, s5, 2
	v_accvgpr_read_b32 v74, a72
	v_mov_b32_e32 v179, v65
	v_lshl_add_u64 v[140:141], v[74:75], 0, s[88:89]
	s_movk_i32 s5, 0x1000
	v_mov_b32_e32 v181, v65
	v_add_co_u32_e32 v142, vcc, s5, v140
	v_mov_b32_e32 v183, v65
	s_nop 0
	v_addc_co_u32_e32 v143, vcc, 0, v141, vcc
	v_accvgpr_write_b32 a57, v108
	v_mov_b32_e32 v185, v65
	v_mov_b32_e32 v187, v65
	v_accvgpr_write_b32 a58, v109
	v_lshlrev_b32_e32 v74, 2, v196
	v_accvgpr_write_b32 a55, v104
	v_accvgpr_write_b32 a56, v105
	v_accvgpr_write_b32 a48, v106
	v_accvgpr_write_b32 a59, v110
	s_waitcnt vmcnt(0)
	v_lshlrev_b32_e32 v5, 16, v5
	v_mul_f32_e32 v5, v6, v5
	v_cvt_pk_bf16_f32 v5, v5, s0
	ds_write_b16 v135, v5 offset:52736
	s_waitcnt vmcnt(0)
	v_accvgpr_read_b32 v5, a0
	v_accvgpr_read_b32 v6, a1
	v_accvgpr_write_b32 a60, v111
	v_accvgpr_write_b32 a61, v112
	s_mov_b64 s[80:81], 0
	v_accvgpr_write_b32 a77, v139
	s_waitcnt vmcnt(1)
	v_lshlrev_b32_e32 v5, 16, v5
	v_mul_f32_e32 v4, v4, v5
	v_cvt_pk_bf16_f32 v4, v4, s0
	ds_write_b16 v135, v4 offset:61952
	ds_read2_b32 v[4:5], v104 offset0:64 offset1:129
	s_waitcnt vmcnt(0)
	v_lshlrev_b32_e32 v6, 16, v6
	s_waitcnt lgkmcnt(0)
	v_mul_f32_e32 v7, 0x3fb8aa3b, v4
	v_exp_f32_e32 v7, v7
	v_mul_f32_e32 v4, 0xbfb8aa3b, v4
	v_exp_f32_e32 v4, v4
	v_mul_f32_e32 v6, v7, v6
	v_cvt_pk_bf16_f32 v6, v6, s0
	ds_write_b16 v254, v6 offset:52736
	v_accvgpr_read_b32 v6, a2
	s_waitcnt vmcnt(0)
	v_lshlrev_b32_e32 v6, 16, v6
	v_mul_f32_e32 v4, v4, v6
	v_cvt_pk_bf16_f32 v4, v4, s0
	ds_write_b16 v254, v4 offset:61952
	v_accvgpr_read_b32 v4, a3
	v_mul_f32_e32 v6, 0x3fb8aa3b, v5
	v_exp_f32_e32 v6, v6
	v_mul_f32_e32 v5, 0xbfb8aa3b, v5
	v_exp_f32_e32 v5, v5
	s_waitcnt vmcnt(0)
	v_lshlrev_b32_e32 v4, 16, v4
	v_mul_f32_e32 v4, v6, v4
	v_cvt_pk_bf16_f32 v4, v4, s0
	ds_write_b16 v106, v4 offset:52736
	v_accvgpr_read_b32 v4, a4
	v_accvgpr_read_b32 v6, a5
	s_waitcnt vmcnt(1)
	v_lshlrev_b32_e32 v4, 16, v4
	v_mul_f32_e32 v4, v5, v4
	v_cvt_pk_bf16_f32 v4, v4, s0
	ds_write_b16 v106, v4 offset:61952
	ds_read2_b32 v[4:5], v105 offset0:66 offset1:131
	s_waitcnt vmcnt(0)
	v_lshlrev_b32_e32 v6, 16, v6
	v_accvgpr_read_b32 v106, a80
	s_waitcnt lgkmcnt(0)
	v_mul_f32_e32 v7, 0x3fb8aa3b, v4
	v_exp_f32_e32 v7, v7
	v_mul_f32_e32 v4, 0xbfb8aa3b, v4
	v_exp_f32_e32 v4, v4
	v_mul_f32_e32 v6, v7, v6
	v_cvt_pk_bf16_f32 v6, v6, s0
	ds_write_b16 v226, v6 offset:52736
	v_accvgpr_read_b32 v6, a6
	s_waitcnt vmcnt(0)
	v_lshlrev_b32_e32 v6, 16, v6
	v_mul_f32_e32 v4, v4, v6
	v_cvt_pk_bf16_f32 v4, v4, s0
	ds_write_b16 v226, v4 offset:61952
	v_lshl_add_u64 v[226:227], v[2:3], 0, v[8:9]
	v_accvgpr_read_b32 v4, a7
	v_mul_f32_e32 v6, 0x3fb8aa3b, v5
	v_exp_f32_e32 v6, v6
	v_accvgpr_read_b32 v8, a92
	v_accvgpr_read_b32 v9, a93
	v_lshl_add_u64 v[236:237], v[2:3], 0, v[8:9]
	v_mul_f32_e32 v5, 0xbfb8aa3b, v5
	v_exp_f32_e32 v5, v5
	s_waitcnt vmcnt(0)
	v_lshlrev_b32_e32 v4, 16, v4
	v_mul_f32_e32 v4, v6, v4
	v_cvt_pk_bf16_f32 v4, v4, s0
	ds_write_b16 v228, v4 offset:52736
	v_accvgpr_read_b32 v4, a8
	v_accvgpr_read_b32 v6, a9
	s_waitcnt vmcnt(1)
	v_lshlrev_b32_e32 v4, 16, v4
	v_mul_f32_e32 v4, v5, v4
	v_cvt_pk_bf16_f32 v4, v4, s0
	ds_write_b16 v228, v4 offset:61952
	ds_read2_b32 v[4:5], v108 offset0:68 offset1:133
	s_waitcnt vmcnt(0)
	v_lshlrev_b32_e32 v6, 16, v6
	v_lshl_add_u64 v[228:229], v[0:1], 0, v[8:9]
	v_accvgpr_read_b32 v8, a94
	v_accvgpr_read_b32 v9, a95
	s_waitcnt lgkmcnt(0)
	v_mul_f32_e32 v7, 0x3fb8aa3b, v4
	v_exp_f32_e32 v7, v7
	v_mul_f32_e32 v4, 0xbfb8aa3b, v4
	v_exp_f32_e32 v4, v4
	v_lshl_add_u64 v[230:231], v[2:3], 0, v[8:9]
	v_mul_f32_e32 v6, v7, v6
	v_cvt_pk_bf16_f32 v6, v6, s0
	ds_write_b16 v202, v6 offset:52736
	v_accvgpr_read_b32 v6, a10
	v_lshl_add_u64 v[234:235], v[0:1], 0, v[8:9]
	v_accvgpr_read_b32 v8, a96
	v_accvgpr_read_b32 v9, a97
	v_lshl_add_u64 v[238:239], v[2:3], 0, v[8:9]
	v_lshl_add_u64 v[240:241], v[0:1], 0, v[8:9]
	v_accvgpr_read_b32 v8, a98
	v_accvgpr_read_b32 v9, a99
	v_lshl_add_u64 v[242:243], v[2:3], 0, v[8:9]
	v_lshl_add_u64 v[244:245], v[0:1], 0, v[8:9]
	v_accvgpr_read_b32 v8, a100
	v_accvgpr_read_b32 v9, a101
	v_lshl_add_u64 v[246:247], v[2:3], 0, v[8:9]
	v_lshl_add_u64 v[248:249], v[0:1], 0, v[8:9]
	v_accvgpr_read_b32 v8, a102
	v_accvgpr_read_b32 v9, a103
	v_lshl_add_u64 v[200:201], v[2:3], 0, v[8:9]
	v_add_co_u32_e32 v108, vcc, s13, v140
	s_waitcnt vmcnt(0)
	v_lshlrev_b32_e32 v6, 16, v6
	v_mul_f32_e32 v4, v4, v6
	v_cvt_pk_bf16_f32 v4, v4, s0
	ds_write_b16 v202, v4 offset:61952
	v_accvgpr_read_b32 v4, a11
	v_mul_f32_e32 v6, 0x3fb8aa3b, v5
	v_exp_f32_e32 v6, v6
	v_mul_f32_e32 v5, 0xbfb8aa3b, v5
	v_exp_f32_e32 v5, v5
	s_waitcnt vmcnt(0)
	v_lshlrev_b32_e32 v4, 16, v4
	v_mul_f32_e32 v4, v6, v4
	v_cvt_pk_bf16_f32 v4, v4, s0
	ds_write_b16 v203, v4 offset:52736
	v_accvgpr_read_b32 v4, a12
	v_accvgpr_read_b32 v6, a13
	s_waitcnt vmcnt(1)
	v_lshlrev_b32_e32 v4, 16, v4
	v_mul_f32_e32 v4, v5, v4
	v_cvt_pk_bf16_f32 v4, v4, s0
	ds_write_b16 v203, v4 offset:61952
	ds_read2_b32 v[4:5], v109 offset0:70 offset1:135
	s_waitcnt vmcnt(0)
	v_lshlrev_b32_e32 v6, 16, v6
	v_lshl_add_u64 v[202:203], v[0:1], 0, v[8:9]
	v_accvgpr_read_b32 v8, a104
	v_accvgpr_read_b32 v9, a105
	s_waitcnt lgkmcnt(0)
	v_mul_f32_e32 v7, 0x3fb8aa3b, v4
	v_exp_f32_e32 v7, v7
	v_mul_f32_e32 v4, 0xbfb8aa3b, v4
	v_exp_f32_e32 v4, v4
	v_lshl_add_u64 v[208:209], v[0:1], 0, v[8:9]
	v_mul_f32_e32 v6, v7, v6
	v_cvt_pk_bf16_f32 v6, v6, s0
	ds_write_b16 v204, v6 offset:52736
	v_accvgpr_read_b32 v6, a14
	v_addc_co_u32_e32 v109, vcc, 0, v141, vcc
	s_waitcnt vmcnt(0)
	v_lshlrev_b32_e32 v6, 16, v6
	v_mul_f32_e32 v4, v4, v6
	v_cvt_pk_bf16_f32 v4, v4, s0
	ds_write_b16 v204, v4 offset:61952
	v_accvgpr_read_b32 v4, a15
	v_mul_f32_e32 v6, 0x3fb8aa3b, v5
	v_exp_f32_e32 v6, v6
	v_mul_f32_e32 v5, 0xbfb8aa3b, v5
	v_exp_f32_e32 v5, v5
	v_lshl_add_u64 v[204:205], v[2:3], 0, v[8:9]
	v_accvgpr_read_b32 v8, a106
	v_accvgpr_read_b32 v9, a107
	v_lshl_add_u64 v[210:211], v[2:3], 0, v[8:9]
	v_lshl_add_u64 v[212:213], v[0:1], 0, v[8:9]
	v_accvgpr_read_b32 v8, a108
	v_accvgpr_read_b32 v9, a109
	v_lshl_add_u64 v[214:215], v[2:3], 0, v[8:9]
	v_lshl_add_u64 v[216:217], v[0:1], 0, v[8:9]
	v_accvgpr_read_b32 v8, a110
	v_accvgpr_read_b32 v9, a111
	v_lshl_add_u64 v[218:219], v[2:3], 0, v[8:9]
	v_lshl_add_u64 v[220:221], v[0:1], 0, v[8:9]
	s_waitcnt vmcnt(0)
	v_lshlrev_b32_e32 v4, 16, v4
	v_mul_f32_e32 v4, v6, v4
	v_cvt_pk_bf16_f32 v4, v4, s0
	ds_write_b16 v73, v4 offset:52736
	v_accvgpr_read_b32 v4, a16
	v_accvgpr_read_b32 v6, a17
	s_waitcnt vmcnt(1)
	v_lshlrev_b32_e32 v4, 16, v4
	v_mul_f32_e32 v4, v5, v4
	v_cvt_pk_bf16_f32 v4, v4, s0
	ds_write_b16 v73, v4 offset:61952
	ds_read2_b32 v[4:5], v110 offset0:72 offset1:137
	s_waitcnt vmcnt(0)
	v_lshlrev_b32_e32 v6, 16, v6
	s_waitcnt lgkmcnt(0)
	v_mul_f32_e32 v7, 0x3fb8aa3b, v4
	v_exp_f32_e32 v7, v7
	v_mul_f32_e32 v4, 0xbfb8aa3b, v4
	v_exp_f32_e32 v4, v4
	v_mul_f32_e32 v6, v7, v6
	v_cvt_pk_bf16_f32 v6, v6, s0
	ds_write_b16 v128, v6 offset:52736
	v_accvgpr_read_b32 v6, a18
	s_waitcnt vmcnt(0)
	v_lshlrev_b32_e32 v6, 16, v6
	v_mul_f32_e32 v4, v4, v6
	v_cvt_pk_bf16_f32 v4, v4, s0
	ds_write_b16 v128, v4 offset:61952
	v_accvgpr_read_b32 v4, a19
	v_mul_f32_e32 v6, 0x3fb8aa3b, v5
	v_exp_f32_e32 v6, v6
	v_mul_f32_e32 v5, 0xbfb8aa3b, v5
	v_exp_f32_e32 v5, v5
	s_waitcnt vmcnt(0)
	v_lshlrev_b32_e32 v4, 16, v4
	v_mul_f32_e32 v4, v6, v4
	v_cvt_pk_bf16_f32 v4, v4, s0
	ds_write_b16 v107, v4 offset:52736
	v_accvgpr_read_b32 v4, a20
	v_accvgpr_read_b32 v6, a21
	s_waitcnt vmcnt(1)
	v_lshlrev_b32_e32 v4, 16, v4
	v_mul_f32_e32 v4, v5, v4
	v_cvt_pk_bf16_f32 v4, v4, s0
	ds_write_b16 v107, v4 offset:61952
	ds_read2_b32 v[4:5], v111 offset0:74 offset1:139
	s_waitcnt vmcnt(0)
	v_lshlrev_b32_e32 v6, 16, v6
	s_waitcnt lgkmcnt(0)
	v_mul_f32_e32 v7, 0x3fb8aa3b, v4
	v_exp_f32_e32 v7, v7
	v_mul_f32_e32 v4, 0xbfb8aa3b, v4
	v_exp_f32_e32 v4, v4
	v_mul_f32_e32 v6, v7, v6
	v_cvt_pk_bf16_f32 v6, v6, s0
	ds_write_b16 v78, v6 offset:52736
	v_accvgpr_read_b32 v6, a22
	s_waitcnt vmcnt(0)
	v_lshlrev_b32_e32 v6, 16, v6
	v_mul_f32_e32 v4, v4, v6
	v_cvt_pk_bf16_f32 v4, v4, s0
	ds_write_b16 v78, v4 offset:61952
	v_accvgpr_read_b32 v4, a23
	v_mul_f32_e32 v6, 0x3fb8aa3b, v5
	v_exp_f32_e32 v6, v6
	v_mul_f32_e32 v5, 0xbfb8aa3b, v5
	v_exp_f32_e32 v5, v5
	s_waitcnt vmcnt(0)
	v_lshlrev_b32_e32 v4, 16, v4
	v_mul_f32_e32 v4, v6, v4
	v_cvt_pk_bf16_f32 v4, v4, s0
	ds_write_b16 v79, v4 offset:52736
	v_accvgpr_read_b32 v4, a24
	v_accvgpr_read_b32 v6, a25
	s_waitcnt vmcnt(1)
	v_lshlrev_b32_e32 v4, 16, v4
	v_mul_f32_e32 v4, v5, v4
	v_cvt_pk_bf16_f32 v4, v4, s0
	ds_write_b16 v79, v4 offset:61952
	ds_read2_b32 v[4:5], v112 offset0:76 offset1:141
	s_waitcnt vmcnt(0)
	v_lshlrev_b32_e32 v6, 16, v6
	s_waitcnt lgkmcnt(0)
	v_mul_f32_e32 v7, 0x3fb8aa3b, v4
	v_exp_f32_e32 v7, v7
	v_mul_f32_e32 v4, 0xbfb8aa3b, v4
	v_exp_f32_e32 v4, v4
	v_mul_f32_e32 v6, v7, v6
	v_cvt_pk_bf16_f32 v6, v6, s0
	ds_write_b16 v129, v6 offset:52736
	v_accvgpr_read_b32 v6, a26
	s_waitcnt vmcnt(0)
	v_lshlrev_b32_e32 v6, 16, v6
	v_mul_f32_e32 v4, v4, v6
	v_cvt_pk_bf16_f32 v4, v4, s0
	ds_write_b16 v129, v4 offset:61952
	v_accvgpr_read_b32 v4, a27
	v_mul_f32_e32 v6, 0x3fb8aa3b, v5
	v_exp_f32_e32 v6, v6
	v_mul_f32_e32 v5, 0xbfb8aa3b, v5
	v_exp_f32_e32 v5, v5
	s_waitcnt vmcnt(0)
	v_lshlrev_b32_e32 v4, 16, v4
	v_mul_f32_e32 v4, v6, v4
	v_cvt_pk_bf16_f32 v4, v4, s0
	ds_write_b16 v68, v4 offset:52736
	v_accvgpr_read_b32 v4, a28
	v_accvgpr_read_b32 v6, a112
	v_accvgpr_read_b32 v7, a113
	v_lshl_add_u64 v[250:251], v[2:3], 0, v[6:7]
	v_lshl_add_u64 v[252:253], v[0:1], 0, v[6:7]
	v_accvgpr_read_b32 v2, a29
	v_accvgpr_read_b32 v0, a30
	s_waitcnt vmcnt(2)
	v_lshlrev_b32_e32 v4, 16, v4
	v_mul_f32_e32 v4, v5, v4
	v_cvt_pk_bf16_f32 v4, v4, s0
	ds_write_b16 v68, v4 offset:61952
	v_accvgpr_read_b32 v4, a81
	ds_read_b32 v4, v4 offset:39736
	s_waitcnt vmcnt(1)
	v_lshlrev_b32_e32 v2, 16, v2
	s_waitcnt vmcnt(0)
	v_lshlrev_b32_e32 v0, 16, v0
	s_waitcnt lgkmcnt(0)
	v_mul_f32_e32 v3, 0x3fb8aa3b, v4
	v_mul_f32_e32 v1, 0xbfb8aa3b, v4
	v_exp_f32_e32 v3, v3
	v_exp_f32_e32 v1, v1
	v_mul_f32_e32 v2, v3, v2
	v_mul_f32_e32 v0, v1, v0
	v_cvt_pk_bf16_f32 v2, v2, s0
	v_cvt_pk_bf16_f32 v0, v0, s0
	ds_write_b16 v69, v2 offset:52736
	ds_write_b16 v69, v0 offset:61952
	s_waitcnt lgkmcnt(0)
	s_barrier
	ds_read_b128 v[4:7], v132 offset:52736
	ds_read_b128 v[0:3], v132 offset:52768
	ds_read_b128 v[24:27], v133 offset:61952
	ds_read_b128 v[12:15], v133 offset:61984
	ds_read_b128 v[8:11], v132 offset:52800
	ds_read_b128 v[16:19], v133 offset:62016
	ds_read_b128 v[20:23], v132 offset:52832
	ds_read_b128 v[28:31], v133 offset:62048
	global_load_dword v67, v[32:33], off
	global_load_dword v81, v[32:33], off offset:512
	global_load_dword v85, v[32:33], off offset:1024
	global_load_dword v115, v[32:33], off offset:1536
	global_load_dword v119, v[32:33], off offset:2048
	global_load_dword v136, v[32:33], off offset:2560
	global_load_dword v137, v[32:33], off offset:3072
	global_load_dword v98, v[32:33], off offset:3584
	ds_read_b128 v[36:39], v82 offset:52736
	ds_read_b128 v[32:35], v82 offset:52768
	ds_read_b128 v[40:43], v82 offset:57344
	global_load_dword v121, v[44:45], off
	global_load_dword v157, v[48:49], off
	v_lshl_add_u64 v[44:45], v[56:57], 0, v[122:123]
	v_lshl_add_u64 v[48:49], v[56:57], 0, v[158:159]
	global_load_dword v123, v[44:45], off
	global_load_dword v159, v[48:49], off
	v_lshl_add_u64 v[44:45], v[56:57], 0, v[124:125]
	v_lshl_add_u64 v[48:49], v[56:57], 0, v[160:161]
	global_load_dword v125, v[44:45], off
	global_load_dword v161, v[48:49], off
	v_lshl_add_u64 v[44:45], v[56:57], 0, v[126:127]
	v_lshl_add_u64 v[48:49], v[56:57], 0, v[162:163]
	global_load_dword v127, v[44:45], off
	global_load_dword v163, v[48:49], off
	v_lshl_add_u64 v[44:45], v[56:57], 0, v[148:149]
	v_lshl_add_u64 v[48:49], v[56:57], 0, v[164:165]
	global_load_dword v149, v[44:45], off
	global_load_dword v165, v[48:49], off
	v_lshl_add_u64 v[44:45], v[56:57], 0, v[150:151]
	v_lshl_add_u64 v[48:49], v[56:57], 0, v[166:167]
	global_load_dword v151, v[44:45], off
	global_load_dword v167, v[48:49], off
	v_lshl_add_u64 v[44:45], v[56:57], 0, v[152:153]
	v_lshl_add_u64 v[48:49], v[56:57], 0, v[168:169]
	global_load_dword v153, v[44:45], off
	global_load_dword v169, v[48:49], off
	v_lshl_add_u64 v[44:45], v[56:57], 0, v[154:155]
	v_lshl_add_u64 v[48:49], v[56:57], 0, v[170:171]
	global_load_dword v155, v[44:45], off
	global_load_dword v171, v[48:49], off
	ds_read_b128 v[44:47], v82 offset:57376
	ds_read_b128 v[52:55], v82 offset:52800
	ds_read_b128 v[48:51], v82 offset:57408
	global_load_dword v173, v[58:59], off
	v_lshl_add_u64 v[58:59], v[56:57], 0, v[174:175]
	global_load_dword v175, v[58:59], off
	v_lshl_add_u64 v[58:59], v[56:57], 0, v[176:177]
	global_load_dword v177, v[58:59], off
	v_lshl_add_u64 v[58:59], v[56:57], 0, v[178:179]
	global_load_dword v179, v[58:59], off
	v_lshl_add_u64 v[58:59], v[56:57], 0, v[180:181]
	global_load_dword v181, v[58:59], off
	v_lshl_add_u64 v[58:59], v[56:57], 0, v[182:183]
	global_load_dword v183, v[58:59], off
	v_lshl_add_u64 v[58:59], v[56:57], 0, v[184:185]
	v_lshl_add_u64 v[56:57], v[56:57], 0, v[186:187]
	global_load_dword v185, v[58:59], off
	global_load_dword v187, v[56:57], off
	ds_read_b128 v[60:63], v82 offset:52832
	ds_read_b128 v[56:59], v82 offset:57440
	s_waitcnt lgkmcnt(0)
	s_barrier
	global_load_dword v99, v74, s[82:83] offset:1024
	global_load_dword v100, v[140:141], off
	global_load_dword v101, v[140:141], off offset:1024
	global_load_dword v102, v[140:141], off offset:2048
	global_load_dword v103, v[140:141], off offset:3072
	global_load_dword v104, v[108:109], off offset:-4096
	global_load_dword v105, v[142:143], off offset:1024
	global_load_dword v196, v[142:143], off offset:2048
	global_load_dword v197, v[142:143], off offset:3072
	global_load_dword v146, v[108:109], off
	global_load_dword v147, v[108:109], off offset:1024
	global_load_dword v144, v[108:109], off offset:2048
	global_load_dword v145, v[108:109], off offset:3072
	v_add_co_u32_e32 v108, vcc, 0x3000, v140
	s_nop 1
	v_addc_co_u32_e32 v109, vcc, 0, v141, vcc
	global_load_dword v140, v[108:109], off
	global_load_dword v141, v[108:109], off offset:1024
	global_load_dword v142, v[108:109], off offset:2048
	global_load_dword v143, v[108:109], off offset:3072
	v_accvgpr_read_b32 v108, a79
